# FFN-down L0 tail round: 64 tail tiles split 4-way along K over all 256 workgroups, f32 partials via dead H2 region, last-arriving wave sums in fixed order + normal bf16 epilogue (on top of non-scaled
# baseline (speedup 1.0000x reference)
.LBB0_1386:
	s_add_i32 s65, s24, 1
	s_mul_i32 s0, s65, s60
	s_mul_hi_u32 s1, s65, s36
	s_add_i32 s1, s1, s0
	s_mul_i32 s0, s65, s36
	s_cmp_eq_u32 s36, 0x100
	s_cselect_b32 s99, 2, -1
	s_and_b32 s98, s37, 63
	s_cmp_eq_u32 s65, s99
	s_cselect_b32 s98, s98, s37
	s_add_u32 s2, s0, s98
	s_addc_u32 s3, s1, s42
	v_cmp_gt_i64_e32 vcc, s[2:3], v[208:209]
	v_cmp_lt_i64_e64 s[0:1], s[2:3], v[206:207]
	s_cbranch_vccnz .LBB0_1391
	s_ashr_i32 s3, s2, 31
	s_lshr_b32 s3, s3, 29
	s_add_i32 s3, s2, s3
	s_ashr_i32 s20, s3, 3
	s_and_b32 s3, s3, -8
	s_sub_i32 s2, s2, s3
	s_cmp_lt_i32 s2, 0
	s_cselect_b32 s3, s43, 0x48
	s_mul_i32 s2, s3, s2
	s_add_i32 s20, s2, s20
	s_cmpk_lt_i32 s20, 0x240
	s_mov_b64 s[2:3], -1
	s_cbranch_scc1 .LBB0_1389
	s_add_i32 s2, s20, 0xfffffdc0
	s_mul_hi_u32 s3, s2, 0x51eb851f
	s_lshr_b32 s3, s3, 3
	s_mul_i32 s21, s3, 0xffffffe7
	s_add_i32 s21, s21, s2
	s_mul_i32 s2, s3, 9
	s_add_i32 s66, s2, 8
	s_cmp_gt_i32 s21, 19
	s_cselect_b32 s2, 26, 19
	s_cmp_gt_i32 s21, 2
	s_cselect_b32 s2, s2, 12
	s_add_i32 s67, s2, s21
	s_mov_b64 s[2:3], 0

.LBB0_1395:
	s_movk_i32 s100, 0x2b00
	s_movk_i32 s101, 0x55
	s_cmp_eq_u32 s36, 0x100
	s_cbranch_scc0 .Lsk12_c
	s_cmp_eq_u32 s65, 3
	s_cbranch_scc0 .Lsk12_b
	s_movk_i32 s100, 0xa00
	s_movk_i32 s101, 19
.Lsk12_b:
	s_cmp_eq_u32 s65, 2
	s_cbranch_scc0 .Lsk12_c
	s_lshr_b32 s99, s37, 6
	s_mul_i32 s99, s99, 0xb00
	s_add_u32 s0, s0, s99
	s_addc_u32 s1, s1, 0
	s_add_u32 s20, s20, s99
	s_addc_u32 s21, s21, 0

.LBB0_1397:
	s_waitcnt lgkmcnt(0)
	s_barrier
	s_setprio 1
	s_waitcnt lgkmcnt(0)
	v_mfma_f32_16x16x32_bf16 v[62:65], v[146:149], v[186:189], v[62:65]
	v_mfma_f32_16x16x32_bf16 v[58:61], v[154:157], v[186:189], v[58:61]
	v_mfma_f32_16x16x32_bf16 v[54:57], v[146:149], v[178:181], v[54:57]
	v_mfma_f32_16x16x32_bf16 v[46:49], v[154:157], v[178:181], v[46:49]
	v_mfma_f32_16x16x32_bf16 v[38:41], v[146:149], v[170:173], v[38:41]
	v_mfma_f32_16x16x32_bf16 v[30:33], v[154:157], v[170:173], v[30:33]
	v_mfma_f32_16x16x32_bf16 v[22:25], v[146:149], v[162:165], v[22:25]
	v_mfma_f32_16x16x32_bf16 v[14:17], v[154:157], v[162:165], v[14:17]
	v_mfma_f32_16x16x32_bf16 v[62:65], v[150:153], v[190:193], v[62:65]
	v_mfma_f32_16x16x32_bf16 v[58:61], v[158:161], v[190:193], v[58:61]
	v_mfma_f32_16x16x32_bf16 v[54:57], v[150:153], v[182:185], v[54:57]
	v_mfma_f32_16x16x32_bf16 v[46:49], v[158:161], v[182:185], v[46:49]
	v_mfma_f32_16x16x32_bf16 v[38:41], v[150:153], v[174:177], v[38:41]
	v_mfma_f32_16x16x32_bf16 v[30:33], v[158:161], v[174:177], v[30:33]
	v_mfma_f32_16x16x32_bf16 v[22:25], v[150:153], v[166:169], v[22:25]
	v_mfma_f32_16x16x32_bf16 v[14:17], v[158:161], v[166:169], v[14:17]
	s_setprio 0
	s_setprio 1
	v_mfma_f32_16x16x32_bf16 v[50:53], v[130:133], v[186:189], v[50:53]
	v_mfma_f32_16x16x32_bf16 v[42:45], v[138:141], v[186:189], v[42:45]
	v_mfma_f32_16x16x32_bf16 v[34:37], v[130:133], v[178:181], v[34:37]
	v_mfma_f32_16x16x32_bf16 v[26:29], v[138:141], v[178:181], v[26:29]
	v_mfma_f32_16x16x32_bf16 v[18:21], v[130:133], v[170:173], v[18:21]
	v_mfma_f32_16x16x32_bf16 v[10:13], v[138:141], v[170:173], v[10:13]
	v_mfma_f32_16x16x32_bf16 v[6:9], v[130:133], v[162:165], v[6:9]
	v_mfma_f32_16x16x32_bf16 v[2:5], v[138:141], v[162:165], v[2:5]
	v_mfma_f32_16x16x32_bf16 v[50:53], v[134:137], v[190:193], v[50:53]
	v_mfma_f32_16x16x32_bf16 v[42:45], v[142:145], v[190:193], v[42:45]
	v_mfma_f32_16x16x32_bf16 v[34:37], v[134:137], v[182:185], v[34:37]
	v_mfma_f32_16x16x32_bf16 v[26:29], v[142:145], v[182:185], v[26:29]
	v_mfma_f32_16x16x32_bf16 v[18:21], v[134:137], v[174:177], v[18:21]
	v_mfma_f32_16x16x32_bf16 v[10:13], v[142:145], v[174:177], v[10:13]
	v_mfma_f32_16x16x32_bf16 v[6:9], v[134:137], v[166:169], v[6:9]
	v_mfma_f32_16x16x32_bf16 v[2:5], v[142:145], v[166:169], v[2:5]
	s_setprio 0
	s_barrier
	v_add_u32_e32 v142, s52, v222
	v_add_u32_e32 v158, s57, v222
	ds_read_b128 v[130:133], v142
	ds_read_b128 v[134:137], v142 offset:1024
	ds_read_b128 v[138:141], v142 offset:2048
	ds_read_b128 v[142:145], v142 offset:3072
	ds_read_b128 v[146:149], v158
	ds_read_b128 v[150:153], v158 offset:1024
	ds_read_b128 v[154:157], v158 offset:2048
	ds_read_b128 v[158:161], v158 offset:3072
	s_add_u32 s30, s30, 0x160000
	s_addc_u32 s31, s31, 0
	s_mov_b32 m0, s50
	v_lshl_add_u64 v[228:229], s[30:31], 0, v[200:201]
	ds_read_b128 v[162:165], v226 offset:32768
	ds_read_b128 v[166:169], v226 offset:33792
	ds_read_b128 v[170:173], v226 offset:34816
	ds_read_b128 v[174:177], v226 offset:35840
	ds_read_b128 v[178:181], v226 offset:36864
	ds_read_b128 v[182:185], v226 offset:37888
	ds_read_b128 v[186:189], v226 offset:38912
	ds_read_b128 v[190:193], v226 offset:39936
	global_load_lds_dwordx4 v[228:229], off
	v_lshl_add_u64 v[228:229], s[30:31], 0, v[196:197]
	s_mov_b32 m0, s51
	s_nop 0
	global_load_lds_dwordx4 v[228:229], off
	s_waitcnt vmcnt(8)
	s_waitcnt lgkmcnt(0)
	s_barrier
	s_setprio 1
	s_waitcnt lgkmcnt(0)
	v_mfma_f32_16x16x32_bf16 v[126:129], v[130:133], v[162:165], v[126:129]
	v_mfma_f32_16x16x32_bf16 v[122:125], v[138:141], v[162:165], v[122:125]
	v_mfma_f32_16x16x32_bf16 v[118:121], v[130:133], v[170:173], v[118:121]
	v_mfma_f32_16x16x32_bf16 v[110:113], v[138:141], v[170:173], v[110:113]
	v_mfma_f32_16x16x32_bf16 v[102:105], v[130:133], v[178:181], v[102:105]
	v_mfma_f32_16x16x32_bf16 v[94:97], v[138:141], v[178:181], v[94:97]
	v_mfma_f32_16x16x32_bf16 v[86:89], v[130:133], v[186:189], v[86:89]
	v_mfma_f32_16x16x32_bf16 v[78:81], v[138:141], v[186:189], v[78:81]
	v_mfma_f32_16x16x32_bf16 v[126:129], v[134:137], v[166:169], v[126:129]
	v_mfma_f32_16x16x32_bf16 v[122:125], v[142:145], v[166:169], v[122:125]
	v_mfma_f32_16x16x32_bf16 v[118:121], v[134:137], v[174:177], v[118:121]
	v_mfma_f32_16x16x32_bf16 v[110:113], v[142:145], v[174:177], v[110:113]
	v_mfma_f32_16x16x32_bf16 v[102:105], v[134:137], v[182:185], v[102:105]
	v_mfma_f32_16x16x32_bf16 v[94:97], v[142:145], v[182:185], v[94:97]
	v_mfma_f32_16x16x32_bf16 v[86:89], v[134:137], v[190:193], v[86:89]
	v_mfma_f32_16x16x32_bf16 v[78:81], v[142:145], v[190:193], v[78:81]
	s_setprio 0
	s_setprio 1
	v_mfma_f32_16x16x32_bf16 v[114:117], v[146:149], v[162:165], v[114:117]
	v_mfma_f32_16x16x32_bf16 v[106:109], v[154:157], v[162:165], v[106:109]
	v_mfma_f32_16x16x32_bf16 v[98:101], v[146:149], v[170:173], v[98:101]
	v_mfma_f32_16x16x32_bf16 v[90:93], v[154:157], v[170:173], v[90:93]
	v_mfma_f32_16x16x32_bf16 v[82:85], v[146:149], v[178:181], v[82:85]
	v_mfma_f32_16x16x32_bf16 v[74:77], v[154:157], v[178:181], v[74:77]
	v_mfma_f32_16x16x32_bf16 v[70:73], v[146:149], v[186:189], v[70:73]
	v_mfma_f32_16x16x32_bf16 v[66:69], v[154:157], v[186:189], v[66:69]
	v_mfma_f32_16x16x32_bf16 v[114:117], v[150:153], v[166:169], v[114:117]
	v_mfma_f32_16x16x32_bf16 v[106:109], v[158:161], v[166:169], v[106:109]
	v_mfma_f32_16x16x32_bf16 v[98:101], v[150:153], v[174:177], v[98:101]
	v_mfma_f32_16x16x32_bf16 v[90:93], v[158:161], v[174:177], v[90:93]
	v_mfma_f32_16x16x32_bf16 v[82:85], v[150:153], v[182:185], v[82:85]
	v_mfma_f32_16x16x32_bf16 v[74:77], v[158:161], v[182:185], v[74:77]
	v_mfma_f32_16x16x32_bf16 v[70:73], v[150:153], v[190:193], v[70:73]
	v_mfma_f32_16x16x32_bf16 v[66:69], v[158:161], v[190:193], v[66:69]
	s_setprio 0
	s_barrier
	s_mov_b32 m0, s53
	v_lshl_add_u64 v[214:215], v[214:215], 0, s[8:9]
	s_add_u32 s28, s28, 0x160080
	ds_read_b128 v[162:165], v226 offset:49152
	ds_read_b128 v[166:169], v226 offset:50176
	ds_read_b128 v[170:173], v226 offset:51200
	ds_read_b128 v[174:177], v226 offset:52224
	ds_read_b128 v[178:181], v226 offset:53248
	ds_read_b128 v[182:185], v226 offset:54272
	ds_read_b128 v[186:189], v226 offset:55296
	ds_read_b128 v[190:193], v226 offset:56320
	global_load_lds_dwordx4 v[214:215], off
	v_lshl_add_u64 v[214:215], v[216:217], 0, s[8:9]
	s_mov_b32 m0, s54
	s_addc_u32 s29, s29, 0
	global_load_lds_dwordx4 v[214:215], off
	v_lshl_add_u64 v[214:215], s[28:29], 0, v[198:199]
	s_mov_b32 m0, s58
	s_nop 0
	global_load_lds_dwordx4 v[214:215], off
	v_lshl_add_u64 v[214:215], s[28:29], 0, v[194:195]
	s_mov_b32 m0, s59
	s_nop 0
	global_load_lds_dwordx4 v[214:215], off
	v_lshl_add_u64 v[214:215], v[218:219], 0, s[8:9]
	s_mov_b32 m0, s55
	s_nop 0
	global_load_lds_dwordx4 v[214:215], off
	v_lshl_add_u64 v[214:215], v[220:221], 0, s[8:9]
	s_mov_b32 m0, s56
	s_nop 0
	global_load_lds_dwordx4 v[214:215], off
	s_waitcnt vmcnt(8)
	s_waitcnt lgkmcnt(0)
	s_barrier
	s_setprio 1
	s_waitcnt lgkmcnt(0)
	v_mfma_f32_16x16x32_bf16 v[62:65], v[130:133], v[162:165], v[62:65]
	v_mfma_f32_16x16x32_bf16 v[58:61], v[138:141], v[162:165], v[58:61]
	v_mfma_f32_16x16x32_bf16 v[54:57], v[130:133], v[170:173], v[54:57]
	v_mfma_f32_16x16x32_bf16 v[46:49], v[138:141], v[170:173], v[46:49]
	v_mfma_f32_16x16x32_bf16 v[38:41], v[130:133], v[178:181], v[38:41]
	v_mfma_f32_16x16x32_bf16 v[30:33], v[138:141], v[178:181], v[30:33]
	v_mfma_f32_16x16x32_bf16 v[22:25], v[130:133], v[186:189], v[22:25]
	v_mfma_f32_16x16x32_bf16 v[14:17], v[138:141], v[186:189], v[14:17]
	v_mfma_f32_16x16x32_bf16 v[62:65], v[134:137], v[166:169], v[62:65]
	v_mfma_f32_16x16x32_bf16 v[58:61], v[142:145], v[166:169], v[58:61]
	v_mfma_f32_16x16x32_bf16 v[54:57], v[134:137], v[174:177], v[54:57]
	v_mfma_f32_16x16x32_bf16 v[46:49], v[142:145], v[174:177], v[46:49]
	v_mfma_f32_16x16x32_bf16 v[38:41], v[134:137], v[182:185], v[38:41]
	v_mfma_f32_16x16x32_bf16 v[30:33], v[142:145], v[182:185], v[30:33]
	v_mfma_f32_16x16x32_bf16 v[22:25], v[134:137], v[190:193], v[22:25]
	v_mfma_f32_16x16x32_bf16 v[14:17], v[142:145], v[190:193], v[14:17]
	s_setprio 0
	s_setprio 1
	v_mfma_f32_16x16x32_bf16 v[50:53], v[146:149], v[162:165], v[50:53]
	v_mfma_f32_16x16x32_bf16 v[42:45], v[154:157], v[162:165], v[42:45]
	v_mfma_f32_16x16x32_bf16 v[34:37], v[146:149], v[170:173], v[34:37]
	v_mfma_f32_16x16x32_bf16 v[26:29], v[154:157], v[170:173], v[26:29]
	v_mfma_f32_16x16x32_bf16 v[18:21], v[146:149], v[178:181], v[18:21]
	v_mfma_f32_16x16x32_bf16 v[10:13], v[154:157], v[178:181], v[10:13]
	v_mfma_f32_16x16x32_bf16 v[6:9], v[146:149], v[186:189], v[6:9]
	v_mfma_f32_16x16x32_bf16 v[2:5], v[154:157], v[186:189], v[2:5]
	v_mfma_f32_16x16x32_bf16 v[50:53], v[150:153], v[166:169], v[50:53]
	v_mfma_f32_16x16x32_bf16 v[42:45], v[158:161], v[166:169], v[42:45]
	v_mfma_f32_16x16x32_bf16 v[34:37], v[150:153], v[174:177], v[34:37]
	v_mfma_f32_16x16x32_bf16 v[26:29], v[158:161], v[174:177], v[26:29]
	v_mfma_f32_16x16x32_bf16 v[18:21], v[150:153], v[182:185], v[18:21]
	v_mfma_f32_16x16x32_bf16 v[10:13], v[158:161], v[182:185], v[10:13]
	v_mfma_f32_16x16x32_bf16 v[6:9], v[150:153], v[190:193], v[6:9]
	v_mfma_f32_16x16x32_bf16 v[2:5], v[158:161], v[190:193], v[2:5]
	s_setprio 0
	s_barrier
	s_add_i32 s72, s72, 2
	s_add_u32 s26, s26, 0x100
	s_addc_u32 s27, s27, 0
	s_cmp_gt_u32 s72, s101
	s_cbranch_scc1 .LBB0_1405

.LBB0_1401:
	s_add_u32 s28, s22, s26
	s_addc_u32 s29, s23, s27
	s_add_u32 s28, s28, 0x100
	s_addc_u32 s29, s29, 0
	s_add_u32 s73, s70, s26
	s_addc_u32 s74, s71, s27
	s_waitcnt lgkmcnt(0)
	s_cmp_eq_u32 s26, s100
	s_cselect_b32 s31, s1, s29
	s_cselect_b32 s30, s0, s28
	s_cselect_b32 s29, s21, s74
	s_cselect_b32 s28, s20, s73
	s_barrier
	s_setprio 1
	s_waitcnt lgkmcnt(0)
	v_mfma_f32_16x16x32_bf16 v[126:129], v[146:149], v[186:189], v[126:129]
	v_mfma_f32_16x16x32_bf16 v[122:125], v[154:157], v[186:189], v[122:125]
	v_mfma_f32_16x16x32_bf16 v[118:121], v[146:149], v[178:181], v[118:121]
	v_mfma_f32_16x16x32_bf16 v[110:113], v[154:157], v[178:181], v[110:113]
	v_mfma_f32_16x16x32_bf16 v[102:105], v[146:149], v[170:173], v[102:105]
	v_mfma_f32_16x16x32_bf16 v[94:97], v[154:157], v[170:173], v[94:97]
	v_mfma_f32_16x16x32_bf16 v[86:89], v[146:149], v[162:165], v[86:89]
	v_mfma_f32_16x16x32_bf16 v[78:81], v[154:157], v[162:165], v[78:81]
	v_mfma_f32_16x16x32_bf16 v[126:129], v[150:153], v[190:193], v[126:129]
	v_mfma_f32_16x16x32_bf16 v[122:125], v[158:161], v[190:193], v[122:125]
	v_mfma_f32_16x16x32_bf16 v[118:121], v[150:153], v[182:185], v[118:121]
	v_mfma_f32_16x16x32_bf16 v[110:113], v[158:161], v[182:185], v[110:113]
	v_mfma_f32_16x16x32_bf16 v[102:105], v[150:153], v[174:177], v[102:105]
	v_mfma_f32_16x16x32_bf16 v[94:97], v[158:161], v[174:177], v[94:97]
	v_mfma_f32_16x16x32_bf16 v[86:89], v[150:153], v[166:169], v[86:89]
	v_mfma_f32_16x16x32_bf16 v[78:81], v[158:161], v[166:169], v[78:81]
	s_setprio 0
	s_setprio 1
	v_mfma_f32_16x16x32_bf16 v[114:117], v[130:133], v[186:189], v[114:117]
	v_mfma_f32_16x16x32_bf16 v[106:109], v[138:141], v[186:189], v[106:109]
	v_mfma_f32_16x16x32_bf16 v[98:101], v[130:133], v[178:181], v[98:101]
	v_mfma_f32_16x16x32_bf16 v[90:93], v[138:141], v[178:181], v[90:93]
	v_mfma_f32_16x16x32_bf16 v[82:85], v[130:133], v[170:173], v[82:85]
	v_mfma_f32_16x16x32_bf16 v[74:77], v[138:141], v[170:173], v[74:77]
	v_mfma_f32_16x16x32_bf16 v[70:73], v[130:133], v[162:165], v[70:73]
	v_mfma_f32_16x16x32_bf16 v[66:69], v[138:141], v[162:165], v[66:69]
	v_mfma_f32_16x16x32_bf16 v[114:117], v[134:137], v[190:193], v[114:117]
	v_mfma_f32_16x16x32_bf16 v[106:109], v[142:145], v[190:193], v[106:109]
	v_mfma_f32_16x16x32_bf16 v[98:101], v[134:137], v[182:185], v[98:101]
	v_mfma_f32_16x16x32_bf16 v[90:93], v[142:145], v[182:185], v[90:93]
	v_mfma_f32_16x16x32_bf16 v[82:85], v[134:137], v[174:177], v[82:85]
	v_mfma_f32_16x16x32_bf16 v[74:77], v[142:145], v[174:177], v[74:77]
	v_mfma_f32_16x16x32_bf16 v[70:73], v[134:137], v[166:169], v[70:73]
	v_mfma_f32_16x16x32_bf16 v[66:69], v[142:145], v[166:169], v[66:69]
	s_setprio 0
	s_barrier
	s_mov_b32 m0, s44
	v_lshl_add_u64 v[214:215], s[28:29], 0, v[198:199]
	s_add_u32 s74, s28, 0x160000
	ds_read_b128 v[186:189], v226 offset:16384
	ds_read_b128 v[190:193], v226 offset:17408
	ds_read_b128 v[178:181], v226 offset:18432
	ds_read_b128 v[182:185], v226 offset:19456
	ds_read_b128 v[170:173], v226 offset:20480
	ds_read_b128 v[174:177], v226 offset:21504
	ds_read_b128 v[162:165], v226 offset:22528
	ds_read_b128 v[166:169], v226 offset:23552
	global_load_lds_dwordx4 v[214:215], off
	v_lshl_add_u64 v[216:217], s[28:29], 0, v[194:195]
	s_mov_b32 m0, s45
	s_addc_u32 s75, s29, 0
	global_load_lds_dwordx4 v[216:217], off
	v_lshl_add_u64 v[218:219], s[74:75], 0, v[198:199]
	s_mov_b32 m0, s46
	v_lshl_add_u64 v[220:221], s[30:31], 0, v[196:197]
	global_load_lds_dwordx4 v[218:219], off
	v_lshl_add_u64 v[218:219], s[74:75], 0, v[194:195]
	s_mov_b32 m0, s47
	s_andn2_b64 vcc, exec, s[34:35]
	global_load_lds_dwordx4 v[218:219], off
	v_lshl_add_u64 v[218:219], s[30:31], 0, v[200:201]
	s_mov_b32 m0, s48
	s_nop 0
	global_load_lds_dwordx4 v[218:219], off
	s_mov_b32 m0, s49
	s_nop 0
	global_load_lds_dwordx4 v[220:221], off
	s_cbranch_vccnz .LBB0_1404
	s_waitcnt vmcnt(24)
	s_cbranch_execnz .LBB0_1397
	s_branch .LBB0_1396

.LBB0_1407:
	s_cmp_eq_u32 s36, 0x100
	s_cselect_b32 s99, 3, -1
	s_cmp_eq_u32 s65, s99
	s_cbranch_scc1 .Ltail12

.Ltail12:
	s_nop 15
	s_nop 15
	v_lshlrev_b32_e32 v253, 4, v0
	s_lshl_b32 s98, s37, 18
	s_add_u32 s100, s6, s98
	s_addc_u32 s101, s7, 0
	s_add_u32 s100, s100, 0x4800000
	s_addc_u32 s101, s101, 0
	global_store_dwordx4 v253, v[2:5], s[100:101] sc1
	s_add_u32 s100, s100, 0x2000
	s_addc_u32 s101, s101, 0
	global_store_dwordx4 v253, v[6:9], s[100:101] sc1
	s_add_u32 s100, s100, 0x2000
	s_addc_u32 s101, s101, 0
	global_store_dwordx4 v253, v[10:13], s[100:101] sc1
	s_add_u32 s100, s100, 0x2000
	s_addc_u32 s101, s101, 0
	global_store_dwordx4 v253, v[14:17], s[100:101] sc1
	s_add_u32 s100, s100, 0x2000
	s_addc_u32 s101, s101, 0
	global_store_dwordx4 v253, v[18:21], s[100:101] sc1
	s_add_u32 s100, s100, 0x2000
	s_addc_u32 s101, s101, 0
	global_store_dwordx4 v253, v[22:25], s[100:101] sc1
	s_add_u32 s100, s100, 0x2000
	s_addc_u32 s101, s101, 0
	global_store_dwordx4 v253, v[26:29], s[100:101] sc1
	s_add_u32 s100, s100, 0x2000
	s_addc_u32 s101, s101, 0
	global_store_dwordx4 v253, v[30:33], s[100:101] sc1
	s_add_u32 s100, s100, 0x2000
	s_addc_u32 s101, s101, 0
	global_store_dwordx4 v253, v[34:37], s[100:101] sc1
	s_add_u32 s100, s100, 0x2000
	s_addc_u32 s101, s101, 0
	global_store_dwordx4 v253, v[38:41], s[100:101] sc1
	s_add_u32 s100, s100, 0x2000
	s_addc_u32 s101, s101, 0
	global_store_dwordx4 v253, v[42:45], s[100:101] sc1
	s_add_u32 s100, s100, 0x2000
	s_addc_u32 s101, s101, 0
	global_store_dwordx4 v253, v[46:49], s[100:101] sc1
	s_add_u32 s100, s100, 0x2000
	s_addc_u32 s101, s101, 0
	global_store_dwordx4 v253, v[50:53], s[100:101] sc1
	s_add_u32 s100, s100, 0x2000
	s_addc_u32 s101, s101, 0
	global_store_dwordx4 v253, v[54:57], s[100:101] sc1
	s_add_u32 s100, s100, 0x2000
	s_addc_u32 s101, s101, 0
	global_store_dwordx4 v253, v[58:61], s[100:101] sc1
	s_add_u32 s100, s100, 0x2000
	s_addc_u32 s101, s101, 0
	global_store_dwordx4 v253, v[62:65], s[100:101] sc1
	s_add_u32 s100, s100, 0x2000
	s_addc_u32 s101, s101, 0
	global_store_dwordx4 v253, v[66:69], s[100:101] sc1
	s_add_u32 s100, s100, 0x2000
	s_addc_u32 s101, s101, 0
	global_store_dwordx4 v253, v[70:73], s[100:101] sc1
	s_add_u32 s100, s100, 0x2000
	s_addc_u32 s101, s101, 0
	global_store_dwordx4 v253, v[74:77], s[100:101] sc1
	s_add_u32 s100, s100, 0x2000
	s_addc_u32 s101, s101, 0
	global_store_dwordx4 v253, v[78:81], s[100:101] sc1
	s_add_u32 s100, s100, 0x2000
	s_addc_u32 s101, s101, 0
	global_store_dwordx4 v253, v[82:85], s[100:101] sc1
	s_add_u32 s100, s100, 0x2000
	s_addc_u32 s101, s101, 0
	global_store_dwordx4 v253, v[86:89], s[100:101] sc1
	s_add_u32 s100, s100, 0x2000
	s_addc_u32 s101, s101, 0
	global_store_dwordx4 v253, v[90:93], s[100:101] sc1
	s_add_u32 s100, s100, 0x2000
	s_addc_u32 s101, s101, 0
	global_store_dwordx4 v253, v[94:97], s[100:101] sc1
	s_add_u32 s100, s100, 0x2000
	s_addc_u32 s101, s101, 0
	global_store_dwordx4 v253, v[98:101], s[100:101] sc1
	s_add_u32 s100, s100, 0x2000
	s_addc_u32 s101, s101, 0
	global_store_dwordx4 v253, v[102:105], s[100:101] sc1
	s_add_u32 s100, s100, 0x2000
	s_addc_u32 s101, s101, 0
	global_store_dwordx4 v253, v[106:109], s[100:101] sc1
	s_add_u32 s100, s100, 0x2000
	s_addc_u32 s101, s101, 0
	global_store_dwordx4 v253, v[110:113], s[100:101] sc1
	s_add_u32 s100, s100, 0x2000
	s_addc_u32 s101, s101, 0
	global_store_dwordx4 v253, v[114:117], s[100:101] sc1
	s_add_u32 s100, s100, 0x2000
	s_addc_u32 s101, s101, 0
	global_store_dwordx4 v253, v[118:121], s[100:101] sc1
	s_add_u32 s100, s100, 0x2000
	s_addc_u32 s101, s101, 0
	global_store_dwordx4 v253, v[122:125], s[100:101] sc1
	s_add_u32 s100, s100, 0x2000
	s_addc_u32 s101, s101, 0
	global_store_dwordx4 v253, v[126:129], s[100:101] sc1
	s_add_u32 s100, s100, 0x2000
	s_addc_u32 s101, s101, 0
	s_waitcnt vmcnt(0)
	v_readfirstlane_b32 s98, v0
	s_lshr_b32 s98, s98, 6
	s_and_b32 s99, s37, 63
	s_lshl_b32 s99, s99, 3
	s_add_i32 s98, s98, s99
	s_lshl_b32 s98, s98, 2
	s_add_i32 s98, s98, 0x8000
	s_sub_u32 s100, s6, 0xe600000
	s_subb_u32 s101, s7, 0
	v_mov_b32_e32 v254, s98
	v_mov_b32_e32 v255, 1
	s_mov_b64 exec, 1
	s_nop 3
	global_atomic_add v254, v254, v255, s[100:101] sc0
	s_waitcnt vmcnt(0)
	v_readfirstlane_b32 s98, v254
	s_mov_b64 exec, -1
	s_cmp_eq_u32 s98, 3
	s_cbranch_scc0 .Ltail12_skip
	buffer_inv sc1
	s_waitcnt vmcnt(0)
	s_and_b32 s98, s37, 63
	s_lshl_b32 s98, s98, 18
	s_add_u32 s100, s6, s98
	s_addc_u32 s101, s7, 0
	s_add_u32 s100, s100, 0x4800000
	s_addc_u32 s101, s101, 0
	s_add_u32 s98, s100, 0x3000000
	s_addc_u32 s99, s101, 0
	v_add_u32_e32 v254, 0x1000000, v253
	v_add_u32_e32 v255, 0x2000000, v253
	global_load_dwordx4 v[130:133], v253, s[100:101] sc1
	global_load_dwordx4 v[134:137], v254, s[100:101] sc1
	global_load_dwordx4 v[138:141], v255, s[100:101] sc1
	global_load_dwordx4 v[142:145], v253, s[98:99] sc1
	s_add_u32 s100, s100, 0x2000
	s_addc_u32 s101, s101, 0
	s_add_u32 s98, s98, 0x2000
	s_addc_u32 s99, s99, 0
	global_load_dwordx4 v[146:149], v253, s[100:101] sc1
	global_load_dwordx4 v[150:153], v254, s[100:101] sc1
	global_load_dwordx4 v[154:157], v255, s[100:101] sc1
	global_load_dwordx4 v[158:161], v253, s[98:99] sc1
	s_add_u32 s100, s100, 0x2000
	s_addc_u32 s101, s101, 0
	s_add_u32 s98, s98, 0x2000
	s_addc_u32 s99, s99, 0
	global_load_dwordx4 v[162:165], v253, s[100:101] sc1
	global_load_dwordx4 v[166:169], v254, s[100:101] sc1
	global_load_dwordx4 v[170:173], v255, s[100:101] sc1
	global_load_dwordx4 v[174:177], v253, s[98:99] sc1
	s_add_u32 s100, s100, 0x2000
	s_addc_u32 s101, s101, 0
	s_add_u32 s98, s98, 0x2000
	s_addc_u32 s99, s99, 0
	global_load_dwordx4 v[178:181], v253, s[100:101] sc1
	global_load_dwordx4 v[182:185], v254, s[100:101] sc1
	global_load_dwordx4 v[186:189], v255, s[100:101] sc1
	global_load_dwordx4 v[190:193], v253, s[98:99] sc1
	s_add_u32 s100, s100, 0x2000
	s_addc_u32 s101, s101, 0
	s_add_u32 s98, s98, 0x2000
	s_addc_u32 s99, s99, 0
	s_waitcnt vmcnt(0)
	v_add_f32_e32 v2, v130, v134
	v_add_f32_e32 v3, v131, v135
	v_add_f32_e32 v4, v132, v136
	v_add_f32_e32 v5, v133, v137
	v_add_f32_e32 v2, v2, v138
	v_add_f32_e32 v3, v3, v139
	v_add_f32_e32 v4, v4, v140
	v_add_f32_e32 v5, v5, v141
	v_add_f32_e32 v2, v2, v142
	v_add_f32_e32 v3, v3, v143
	v_add_f32_e32 v4, v4, v144
	v_add_f32_e32 v5, v5, v145
	v_add_f32_e32 v6, v146, v150
	v_add_f32_e32 v7, v147, v151
	v_add_f32_e32 v8, v148, v152
	v_add_f32_e32 v9, v149, v153
	v_add_f32_e32 v6, v6, v154
	v_add_f32_e32 v7, v7, v155
	v_add_f32_e32 v8, v8, v156
	v_add_f32_e32 v9, v9, v157
	v_add_f32_e32 v6, v6, v158
	v_add_f32_e32 v7, v7, v159
	v_add_f32_e32 v8, v8, v160
	v_add_f32_e32 v9, v9, v161
	v_add_f32_e32 v10, v162, v166
	v_add_f32_e32 v11, v163, v167
	v_add_f32_e32 v12, v164, v168
	v_add_f32_e32 v13, v165, v169
	v_add_f32_e32 v10, v10, v170
	v_add_f32_e32 v11, v11, v171
	v_add_f32_e32 v12, v12, v172
	v_add_f32_e32 v13, v13, v173
	v_add_f32_e32 v10, v10, v174
	v_add_f32_e32 v11, v11, v175
	v_add_f32_e32 v12, v12, v176
	v_add_f32_e32 v13, v13, v177
	v_add_f32_e32 v14, v178, v182
	v_add_f32_e32 v15, v179, v183
	v_add_f32_e32 v16, v180, v184
	v_add_f32_e32 v17, v181, v185
	v_add_f32_e32 v14, v14, v186
	v_add_f32_e32 v15, v15, v187
	v_add_f32_e32 v16, v16, v188
	v_add_f32_e32 v17, v17, v189
	v_add_f32_e32 v14, v14, v190
	v_add_f32_e32 v15, v15, v191
	v_add_f32_e32 v16, v16, v192
	v_add_f32_e32 v17, v17, v193
	global_load_dwordx4 v[130:133], v253, s[100:101] sc1
	global_load_dwordx4 v[134:137], v254, s[100:101] sc1
	global_load_dwordx4 v[138:141], v255, s[100:101] sc1
	global_load_dwordx4 v[142:145], v253, s[98:99] sc1
	s_add_u32 s100, s100, 0x2000
	s_addc_u32 s101, s101, 0
	s_add_u32 s98, s98, 0x2000
	s_addc_u32 s99, s99, 0
	global_load_dwordx4 v[146:149], v253, s[100:101] sc1
	global_load_dwordx4 v[150:153], v254, s[100:101] sc1
	global_load_dwordx4 v[154:157], v255, s[100:101] sc1
	global_load_dwordx4 v[158:161], v253, s[98:99] sc1
	s_add_u32 s100, s100, 0x2000
	s_addc_u32 s101, s101, 0
	s_add_u32 s98, s98, 0x2000
	s_addc_u32 s99, s99, 0
	global_load_dwordx4 v[162:165], v253, s[100:101] sc1
	global_load_dwordx4 v[166:169], v254, s[100:101] sc1
	global_load_dwordx4 v[170:173], v255, s[100:101] sc1
	global_load_dwordx4 v[174:177], v253, s[98:99] sc1
	s_add_u32 s100, s100, 0x2000
	s_addc_u32 s101, s101, 0
	s_add_u32 s98, s98, 0x2000
	s_addc_u32 s99, s99, 0
	global_load_dwordx4 v[178:181], v253, s[100:101] sc1
	global_load_dwordx4 v[182:185], v254, s[100:101] sc1
	global_load_dwordx4 v[186:189], v255, s[100:101] sc1
	global_load_dwordx4 v[190:193], v253, s[98:99] sc1
	s_add_u32 s100, s100, 0x2000
	s_addc_u32 s101, s101, 0
	s_add_u32 s98, s98, 0x2000
	s_addc_u32 s99, s99, 0
	s_waitcnt vmcnt(0)
	v_add_f32_e32 v18, v130, v134
	v_add_f32_e32 v19, v131, v135
	v_add_f32_e32 v20, v132, v136
	v_add_f32_e32 v21, v133, v137
	v_add_f32_e32 v18, v18, v138
	v_add_f32_e32 v19, v19, v139
	v_add_f32_e32 v20, v20, v140
	v_add_f32_e32 v21, v21, v141
	v_add_f32_e32 v18, v18, v142
	v_add_f32_e32 v19, v19, v143
	v_add_f32_e32 v20, v20, v144
	v_add_f32_e32 v21, v21, v145
	v_add_f32_e32 v22, v146, v150
	v_add_f32_e32 v23, v147, v151
	v_add_f32_e32 v24, v148, v152
	v_add_f32_e32 v25, v149, v153
	v_add_f32_e32 v22, v22, v154
	v_add_f32_e32 v23, v23, v155
	v_add_f32_e32 v24, v24, v156
	v_add_f32_e32 v25, v25, v157
	v_add_f32_e32 v22, v22, v158
	v_add_f32_e32 v23, v23, v159
	v_add_f32_e32 v24, v24, v160
	v_add_f32_e32 v25, v25, v161
	v_add_f32_e32 v26, v162, v166
	v_add_f32_e32 v27, v163, v167
	v_add_f32_e32 v28, v164, v168
	v_add_f32_e32 v29, v165, v169
	v_add_f32_e32 v26, v26, v170
	v_add_f32_e32 v27, v27, v171
	v_add_f32_e32 v28, v28, v172
	v_add_f32_e32 v29, v29, v173
	v_add_f32_e32 v26, v26, v174
	v_add_f32_e32 v27, v27, v175
	v_add_f32_e32 v28, v28, v176
	v_add_f32_e32 v29, v29, v177
	v_add_f32_e32 v30, v178, v182
	v_add_f32_e32 v31, v179, v183
	v_add_f32_e32 v32, v180, v184
	v_add_f32_e32 v33, v181, v185
	v_add_f32_e32 v30, v30, v186
	v_add_f32_e32 v31, v31, v187
	v_add_f32_e32 v32, v32, v188
	v_add_f32_e32 v33, v33, v189
	v_add_f32_e32 v30, v30, v190
	v_add_f32_e32 v31, v31, v191
	v_add_f32_e32 v32, v32, v192
	v_add_f32_e32 v33, v33, v193
	global_load_dwordx4 v[130:133], v253, s[100:101] sc1
	global_load_dwordx4 v[134:137], v254, s[100:101] sc1
	global_load_dwordx4 v[138:141], v255, s[100:101] sc1
	global_load_dwordx4 v[142:145], v253, s[98:99] sc1
	s_add_u32 s100, s100, 0x2000
	s_addc_u32 s101, s101, 0
	s_add_u32 s98, s98, 0x2000
	s_addc_u32 s99, s99, 0
	global_load_dwordx4 v[146:149], v253, s[100:101] sc1
	global_load_dwordx4 v[150:153], v254, s[100:101] sc1
	global_load_dwordx4 v[154:157], v255, s[100:101] sc1
	global_load_dwordx4 v[158:161], v253, s[98:99] sc1
	s_add_u32 s100, s100, 0x2000
	s_addc_u32 s101, s101, 0
	s_add_u32 s98, s98, 0x2000
	s_addc_u32 s99, s99, 0
	global_load_dwordx4 v[162:165], v253, s[100:101] sc1
	global_load_dwordx4 v[166:169], v254, s[100:101] sc1
	global_load_dwordx4 v[170:173], v255, s[100:101] sc1
	global_load_dwordx4 v[174:177], v253, s[98:99] sc1
	s_add_u32 s100, s100, 0x2000
	s_addc_u32 s101, s101, 0
	s_add_u32 s98, s98, 0x2000
	s_addc_u32 s99, s99, 0
	global_load_dwordx4 v[178:181], v253, s[100:101] sc1
	global_load_dwordx4 v[182:185], v254, s[100:101] sc1
	global_load_dwordx4 v[186:189], v255, s[100:101] sc1
	global_load_dwordx4 v[190:193], v253, s[98:99] sc1
	s_add_u32 s100, s100, 0x2000
	s_addc_u32 s101, s101, 0
	s_add_u32 s98, s98, 0x2000
	s_addc_u32 s99, s99, 0
	s_waitcnt vmcnt(0)
	v_add_f32_e32 v34, v130, v134
	v_add_f32_e32 v35, v131, v135
	v_add_f32_e32 v36, v132, v136
	v_add_f32_e32 v37, v133, v137
	v_add_f32_e32 v34, v34, v138
	v_add_f32_e32 v35, v35, v139
	v_add_f32_e32 v36, v36, v140
	v_add_f32_e32 v37, v37, v141
	v_add_f32_e32 v34, v34, v142
	v_add_f32_e32 v35, v35, v143
	v_add_f32_e32 v36, v36, v144
	v_add_f32_e32 v37, v37, v145
	v_add_f32_e32 v38, v146, v150
	v_add_f32_e32 v39, v147, v151
	v_add_f32_e32 v40, v148, v152
	v_add_f32_e32 v41, v149, v153
	v_add_f32_e32 v38, v38, v154
	v_add_f32_e32 v39, v39, v155
	v_add_f32_e32 v40, v40, v156
	v_add_f32_e32 v41, v41, v157
	v_add_f32_e32 v38, v38, v158
	v_add_f32_e32 v39, v39, v159
	v_add_f32_e32 v40, v40, v160
	v_add_f32_e32 v41, v41, v161
	v_add_f32_e32 v42, v162, v166
	v_add_f32_e32 v43, v163, v167
	v_add_f32_e32 v44, v164, v168
	v_add_f32_e32 v45, v165, v169
	v_add_f32_e32 v42, v42, v170
	v_add_f32_e32 v43, v43, v171
	v_add_f32_e32 v44, v44, v172
	v_add_f32_e32 v45, v45, v173
	v_add_f32_e32 v42, v42, v174
	v_add_f32_e32 v43, v43, v175
	v_add_f32_e32 v44, v44, v176
	v_add_f32_e32 v45, v45, v177
	v_add_f32_e32 v46, v178, v182
	v_add_f32_e32 v47, v179, v183
	v_add_f32_e32 v48, v180, v184
	v_add_f32_e32 v49, v181, v185
	v_add_f32_e32 v46, v46, v186
	v_add_f32_e32 v47, v47, v187
	v_add_f32_e32 v48, v48, v188
	v_add_f32_e32 v49, v49, v189
	v_add_f32_e32 v46, v46, v190
	v_add_f32_e32 v47, v47, v191
	v_add_f32_e32 v48, v48, v192
	v_add_f32_e32 v49, v49, v193
	global_load_dwordx4 v[130:133], v253, s[100:101] sc1
	global_load_dwordx4 v[134:137], v254, s[100:101] sc1
	global_load_dwordx4 v[138:141], v255, s[100:101] sc1
	global_load_dwordx4 v[142:145], v253, s[98:99] sc1
	s_add_u32 s100, s100, 0x2000
	s_addc_u32 s101, s101, 0
	s_add_u32 s98, s98, 0x2000
	s_addc_u32 s99, s99, 0
	global_load_dwordx4 v[146:149], v253, s[100:101] sc1
	global_load_dwordx4 v[150:153], v254, s[100:101] sc1
	global_load_dwordx4 v[154:157], v255, s[100:101] sc1
	global_load_dwordx4 v[158:161], v253, s[98:99] sc1
	s_add_u32 s100, s100, 0x2000
	s_addc_u32 s101, s101, 0
	s_add_u32 s98, s98, 0x2000
	s_addc_u32 s99, s99, 0
	global_load_dwordx4 v[162:165], v253, s[100:101] sc1
	global_load_dwordx4 v[166:169], v254, s[100:101] sc1
	global_load_dwordx4 v[170:173], v255, s[100:101] sc1
	global_load_dwordx4 v[174:177], v253, s[98:99] sc1
	s_add_u32 s100, s100, 0x2000
	s_addc_u32 s101, s101, 0
	s_add_u32 s98, s98, 0x2000
	s_addc_u32 s99, s99, 0
	global_load_dwordx4 v[178:181], v253, s[100:101] sc1
	global_load_dwordx4 v[182:185], v254, s[100:101] sc1
	global_load_dwordx4 v[186:189], v255, s[100:101] sc1
	global_load_dwordx4 v[190:193], v253, s[98:99] sc1
	s_add_u32 s100, s100, 0x2000
	s_addc_u32 s101, s101, 0
	s_add_u32 s98, s98, 0x2000
	s_addc_u32 s99, s99, 0
	s_waitcnt vmcnt(0)
	v_add_f32_e32 v50, v130, v134
	v_add_f32_e32 v51, v131, v135
	v_add_f32_e32 v52, v132, v136
	v_add_f32_e32 v53, v133, v137
	v_add_f32_e32 v50, v50, v138
	v_add_f32_e32 v51, v51, v139
	v_add_f32_e32 v52, v52, v140
	v_add_f32_e32 v53, v53, v141
	v_add_f32_e32 v50, v50, v142
	v_add_f32_e32 v51, v51, v143
	v_add_f32_e32 v52, v52, v144
	v_add_f32_e32 v53, v53, v145
	v_add_f32_e32 v54, v146, v150
	v_add_f32_e32 v55, v147, v151
	v_add_f32_e32 v56, v148, v152
	v_add_f32_e32 v57, v149, v153
	v_add_f32_e32 v54, v54, v154
	v_add_f32_e32 v55, v55, v155
	v_add_f32_e32 v56, v56, v156
	v_add_f32_e32 v57, v57, v157
	v_add_f32_e32 v54, v54, v158
	v_add_f32_e32 v55, v55, v159
	v_add_f32_e32 v56, v56, v160
	v_add_f32_e32 v57, v57, v161
	v_add_f32_e32 v58, v162, v166
	v_add_f32_e32 v59, v163, v167
	v_add_f32_e32 v60, v164, v168
	v_add_f32_e32 v61, v165, v169
	v_add_f32_e32 v58, v58, v170
	v_add_f32_e32 v59, v59, v171
	v_add_f32_e32 v60, v60, v172
	v_add_f32_e32 v61, v61, v173
	v_add_f32_e32 v58, v58, v174
	v_add_f32_e32 v59, v59, v175
	v_add_f32_e32 v60, v60, v176
	v_add_f32_e32 v61, v61, v177
	v_add_f32_e32 v62, v178, v182
	v_add_f32_e32 v63, v179, v183
	v_add_f32_e32 v64, v180, v184
	v_add_f32_e32 v65, v181, v185
	v_add_f32_e32 v62, v62, v186
	v_add_f32_e32 v63, v63, v187
	v_add_f32_e32 v64, v64, v188
	v_add_f32_e32 v65, v65, v189
	v_add_f32_e32 v62, v62, v190
	v_add_f32_e32 v63, v63, v191
	v_add_f32_e32 v64, v64, v192
	v_add_f32_e32 v65, v65, v193
	global_load_dwordx4 v[130:133], v253, s[100:101] sc1
	global_load_dwordx4 v[134:137], v254, s[100:101] sc1
	global_load_dwordx4 v[138:141], v255, s[100:101] sc1
	global_load_dwordx4 v[142:145], v253, s[98:99] sc1
	s_add_u32 s100, s100, 0x2000
	s_addc_u32 s101, s101, 0
	s_add_u32 s98, s98, 0x2000
	s_addc_u32 s99, s99, 0
	global_load_dwordx4 v[146:149], v253, s[100:101] sc1
	global_load_dwordx4 v[150:153], v254, s[100:101] sc1
	global_load_dwordx4 v[154:157], v255, s[100:101] sc1
	global_load_dwordx4 v[158:161], v253, s[98:99] sc1
	s_add_u32 s100, s100, 0x2000
	s_addc_u32 s101, s101, 0
	s_add_u32 s98, s98, 0x2000
	s_addc_u32 s99, s99, 0
	global_load_dwordx4 v[162:165], v253, s[100:101] sc1
	global_load_dwordx4 v[166:169], v254, s[100:101] sc1
	global_load_dwordx4 v[170:173], v255, s[100:101] sc1
	global_load_dwordx4 v[174:177], v253, s[98:99] sc1
	s_add_u32 s100, s100, 0x2000
	s_addc_u32 s101, s101, 0
	s_add_u32 s98, s98, 0x2000
	s_addc_u32 s99, s99, 0
	global_load_dwordx4 v[178:181], v253, s[100:101] sc1
	global_load_dwordx4 v[182:185], v254, s[100:101] sc1
	global_load_dwordx4 v[186:189], v255, s[100:101] sc1
	global_load_dwordx4 v[190:193], v253, s[98:99] sc1
	s_add_u32 s100, s100, 0x2000
	s_addc_u32 s101, s101, 0
	s_add_u32 s98, s98, 0x2000
	s_addc_u32 s99, s99, 0
	s_waitcnt vmcnt(0)
	v_add_f32_e32 v66, v130, v134
	v_add_f32_e32 v67, v131, v135
	v_add_f32_e32 v68, v132, v136
	v_add_f32_e32 v69, v133, v137
	v_add_f32_e32 v66, v66, v138
	v_add_f32_e32 v67, v67, v139
	v_add_f32_e32 v68, v68, v140
	v_add_f32_e32 v69, v69, v141
	v_add_f32_e32 v66, v66, v142
	v_add_f32_e32 v67, v67, v143
	v_add_f32_e32 v68, v68, v144
	v_add_f32_e32 v69, v69, v145
	v_add_f32_e32 v70, v146, v150
	v_add_f32_e32 v71, v147, v151
	v_add_f32_e32 v72, v148, v152
	v_add_f32_e32 v73, v149, v153
	v_add_f32_e32 v70, v70, v154
	v_add_f32_e32 v71, v71, v155
	v_add_f32_e32 v72, v72, v156
	v_add_f32_e32 v73, v73, v157
	v_add_f32_e32 v70, v70, v158
	v_add_f32_e32 v71, v71, v159
	v_add_f32_e32 v72, v72, v160
	v_add_f32_e32 v73, v73, v161
	v_add_f32_e32 v74, v162, v166
	v_add_f32_e32 v75, v163, v167
	v_add_f32_e32 v76, v164, v168
	v_add_f32_e32 v77, v165, v169
	v_add_f32_e32 v74, v74, v170
	v_add_f32_e32 v75, v75, v171
	v_add_f32_e32 v76, v76, v172
	v_add_f32_e32 v77, v77, v173
	v_add_f32_e32 v74, v74, v174
	v_add_f32_e32 v75, v75, v175
	v_add_f32_e32 v76, v76, v176
	v_add_f32_e32 v77, v77, v177
	v_add_f32_e32 v78, v178, v182
	v_add_f32_e32 v79, v179, v183
	v_add_f32_e32 v80, v180, v184
	v_add_f32_e32 v81, v181, v185
	v_add_f32_e32 v78, v78, v186
	v_add_f32_e32 v79, v79, v187
	v_add_f32_e32 v80, v80, v188
	v_add_f32_e32 v81, v81, v189
	v_add_f32_e32 v78, v78, v190
	v_add_f32_e32 v79, v79, v191
	v_add_f32_e32 v80, v80, v192
	v_add_f32_e32 v81, v81, v193
	global_load_dwordx4 v[130:133], v253, s[100:101] sc1
	global_load_dwordx4 v[134:137], v254, s[100:101] sc1
	global_load_dwordx4 v[138:141], v255, s[100:101] sc1
	global_load_dwordx4 v[142:145], v253, s[98:99] sc1
	s_add_u32 s100, s100, 0x2000
	s_addc_u32 s101, s101, 0
	s_add_u32 s98, s98, 0x2000
	s_addc_u32 s99, s99, 0
	global_load_dwordx4 v[146:149], v253, s[100:101] sc1
	global_load_dwordx4 v[150:153], v254, s[100:101] sc1
	global_load_dwordx4 v[154:157], v255, s[100:101] sc1
	global_load_dwordx4 v[158:161], v253, s[98:99] sc1
	s_add_u32 s100, s100, 0x2000
	s_addc_u32 s101, s101, 0
	s_add_u32 s98, s98, 0x2000
	s_addc_u32 s99, s99, 0
	global_load_dwordx4 v[162:165], v253, s[100:101] sc1
	global_load_dwordx4 v[166:169], v254, s[100:101] sc1
	global_load_dwordx4 v[170:173], v255, s[100:101] sc1
	global_load_dwordx4 v[174:177], v253, s[98:99] sc1
	s_add_u32 s100, s100, 0x2000
	s_addc_u32 s101, s101, 0
	s_add_u32 s98, s98, 0x2000
	s_addc_u32 s99, s99, 0
	global_load_dwordx4 v[178:181], v253, s[100:101] sc1
	global_load_dwordx4 v[182:185], v254, s[100:101] sc1
	global_load_dwordx4 v[186:189], v255, s[100:101] sc1
	global_load_dwordx4 v[190:193], v253, s[98:99] sc1
	s_add_u32 s100, s100, 0x2000
	s_addc_u32 s101, s101, 0
	s_add_u32 s98, s98, 0x2000
	s_addc_u32 s99, s99, 0
	s_waitcnt vmcnt(0)
	v_add_f32_e32 v82, v130, v134
	v_add_f32_e32 v83, v131, v135
	v_add_f32_e32 v84, v132, v136
	v_add_f32_e32 v85, v133, v137
	v_add_f32_e32 v82, v82, v138
	v_add_f32_e32 v83, v83, v139
	v_add_f32_e32 v84, v84, v140
	v_add_f32_e32 v85, v85, v141
	v_add_f32_e32 v82, v82, v142
	v_add_f32_e32 v83, v83, v143
	v_add_f32_e32 v84, v84, v144
	v_add_f32_e32 v85, v85, v145
	v_add_f32_e32 v86, v146, v150
	v_add_f32_e32 v87, v147, v151
	v_add_f32_e32 v88, v148, v152
	v_add_f32_e32 v89, v149, v153
	v_add_f32_e32 v86, v86, v154
	v_add_f32_e32 v87, v87, v155
	v_add_f32_e32 v88, v88, v156
	v_add_f32_e32 v89, v89, v157
	v_add_f32_e32 v86, v86, v158
	v_add_f32_e32 v87, v87, v159
	v_add_f32_e32 v88, v88, v160
	v_add_f32_e32 v89, v89, v161
	v_add_f32_e32 v90, v162, v166
	v_add_f32_e32 v91, v163, v167
	v_add_f32_e32 v92, v164, v168
	v_add_f32_e32 v93, v165, v169
	v_add_f32_e32 v90, v90, v170
	v_add_f32_e32 v91, v91, v171
	v_add_f32_e32 v92, v92, v172
	v_add_f32_e32 v93, v93, v173
	v_add_f32_e32 v90, v90, v174
	v_add_f32_e32 v91, v91, v175
	v_add_f32_e32 v92, v92, v176
	v_add_f32_e32 v93, v93, v177
	v_add_f32_e32 v94, v178, v182
	v_add_f32_e32 v95, v179, v183
	v_add_f32_e32 v96, v180, v184
	v_add_f32_e32 v97, v181, v185
	v_add_f32_e32 v94, v94, v186
	v_add_f32_e32 v95, v95, v187
	v_add_f32_e32 v96, v96, v188
	v_add_f32_e32 v97, v97, v189
	v_add_f32_e32 v94, v94, v190
	v_add_f32_e32 v95, v95, v191
	v_add_f32_e32 v96, v96, v192
	v_add_f32_e32 v97, v97, v193
	global_load_dwordx4 v[130:133], v253, s[100:101] sc1
	global_load_dwordx4 v[134:137], v254, s[100:101] sc1
	global_load_dwordx4 v[138:141], v255, s[100:101] sc1
	global_load_dwordx4 v[142:145], v253, s[98:99] sc1
	s_add_u32 s100, s100, 0x2000
	s_addc_u32 s101, s101, 0
	s_add_u32 s98, s98, 0x2000
	s_addc_u32 s99, s99, 0
	global_load_dwordx4 v[146:149], v253, s[100:101] sc1
	global_load_dwordx4 v[150:153], v254, s[100:101] sc1
	global_load_dwordx4 v[154:157], v255, s[100:101] sc1
	global_load_dwordx4 v[158:161], v253, s[98:99] sc1
	s_add_u32 s100, s100, 0x2000
	s_addc_u32 s101, s101, 0
	s_add_u32 s98, s98, 0x2000
	s_addc_u32 s99, s99, 0
	global_load_dwordx4 v[162:165], v253, s[100:101] sc1
	global_load_dwordx4 v[166:169], v254, s[100:101] sc1
	global_load_dwordx4 v[170:173], v255, s[100:101] sc1
	global_load_dwordx4 v[174:177], v253, s[98:99] sc1
	s_add_u32 s100, s100, 0x2000
	s_addc_u32 s101, s101, 0
	s_add_u32 s98, s98, 0x2000
	s_addc_u32 s99, s99, 0
	global_load_dwordx4 v[178:181], v253, s[100:101] sc1
	global_load_dwordx4 v[182:185], v254, s[100:101] sc1
	global_load_dwordx4 v[186:189], v255, s[100:101] sc1
	global_load_dwordx4 v[190:193], v253, s[98:99] sc1
	s_add_u32 s100, s100, 0x2000
	s_addc_u32 s101, s101, 0
	s_add_u32 s98, s98, 0x2000
	s_addc_u32 s99, s99, 0
	s_waitcnt vmcnt(0)
	v_add_f32_e32 v98, v130, v134
	v_add_f32_e32 v99, v131, v135
	v_add_f32_e32 v100, v132, v136
	v_add_f32_e32 v101, v133, v137
	v_add_f32_e32 v98, v98, v138
	v_add_f32_e32 v99, v99, v139
	v_add_f32_e32 v100, v100, v140
	v_add_f32_e32 v101, v101, v141
	v_add_f32_e32 v98, v98, v142
	v_add_f32_e32 v99, v99, v143
	v_add_f32_e32 v100, v100, v144
	v_add_f32_e32 v101, v101, v145
	v_add_f32_e32 v102, v146, v150
	v_add_f32_e32 v103, v147, v151
	v_add_f32_e32 v104, v148, v152
	v_add_f32_e32 v105, v149, v153
	v_add_f32_e32 v102, v102, v154
	v_add_f32_e32 v103, v103, v155
	v_add_f32_e32 v104, v104, v156
	v_add_f32_e32 v105, v105, v157
	v_add_f32_e32 v102, v102, v158
	v_add_f32_e32 v103, v103, v159
	v_add_f32_e32 v104, v104, v160
	v_add_f32_e32 v105, v105, v161
	v_add_f32_e32 v106, v162, v166
	v_add_f32_e32 v107, v163, v167
	v_add_f32_e32 v108, v164, v168
	v_add_f32_e32 v109, v165, v169
	v_add_f32_e32 v106, v106, v170
	v_add_f32_e32 v107, v107, v171
	v_add_f32_e32 v108, v108, v172
	v_add_f32_e32 v109, v109, v173
	v_add_f32_e32 v106, v106, v174
	v_add_f32_e32 v107, v107, v175
	v_add_f32_e32 v108, v108, v176
	v_add_f32_e32 v109, v109, v177
	v_add_f32_e32 v110, v178, v182
	v_add_f32_e32 v111, v179, v183
	v_add_f32_e32 v112, v180, v184
	v_add_f32_e32 v113, v181, v185
	v_add_f32_e32 v110, v110, v186
	v_add_f32_e32 v111, v111, v187
	v_add_f32_e32 v112, v112, v188
	v_add_f32_e32 v113, v113, v189
	v_add_f32_e32 v110, v110, v190
	v_add_f32_e32 v111, v111, v191
	v_add_f32_e32 v112, v112, v192
	v_add_f32_e32 v113, v113, v193
	global_load_dwordx4 v[130:133], v253, s[100:101] sc1
	global_load_dwordx4 v[134:137], v254, s[100:101] sc1
	global_load_dwordx4 v[138:141], v255, s[100:101] sc1
	global_load_dwordx4 v[142:145], v253, s[98:99] sc1
	s_add_u32 s100, s100, 0x2000
	s_addc_u32 s101, s101, 0
	s_add_u32 s98, s98, 0x2000
	s_addc_u32 s99, s99, 0
	global_load_dwordx4 v[146:149], v253, s[100:101] sc1
	global_load_dwordx4 v[150:153], v254, s[100:101] sc1
	global_load_dwordx4 v[154:157], v255, s[100:101] sc1
	global_load_dwordx4 v[158:161], v253, s[98:99] sc1
	s_add_u32 s100, s100, 0x2000
	s_addc_u32 s101, s101, 0
	s_add_u32 s98, s98, 0x2000
	s_addc_u32 s99, s99, 0
	global_load_dwordx4 v[162:165], v253, s[100:101] sc1
	global_load_dwordx4 v[166:169], v254, s[100:101] sc1
	global_load_dwordx4 v[170:173], v255, s[100:101] sc1
	global_load_dwordx4 v[174:177], v253, s[98:99] sc1
	s_add_u32 s100, s100, 0x2000
	s_addc_u32 s101, s101, 0
	s_add_u32 s98, s98, 0x2000
	s_addc_u32 s99, s99, 0
	global_load_dwordx4 v[178:181], v253, s[100:101] sc1
	global_load_dwordx4 v[182:185], v254, s[100:101] sc1
	global_load_dwordx4 v[186:189], v255, s[100:101] sc1
	global_load_dwordx4 v[190:193], v253, s[98:99] sc1
	s_add_u32 s100, s100, 0x2000
	s_addc_u32 s101, s101, 0
	s_add_u32 s98, s98, 0x2000
	s_addc_u32 s99, s99, 0
	s_waitcnt vmcnt(0)
	v_add_f32_e32 v114, v130, v134
	v_add_f32_e32 v115, v131, v135
	v_add_f32_e32 v116, v132, v136
	v_add_f32_e32 v117, v133, v137
	v_add_f32_e32 v114, v114, v138
	v_add_f32_e32 v115, v115, v139
	v_add_f32_e32 v116, v116, v140
	v_add_f32_e32 v117, v117, v141
	v_add_f32_e32 v114, v114, v142
	v_add_f32_e32 v115, v115, v143
	v_add_f32_e32 v116, v116, v144
	v_add_f32_e32 v117, v117, v145
	v_add_f32_e32 v118, v146, v150
	v_add_f32_e32 v119, v147, v151
	v_add_f32_e32 v120, v148, v152
	v_add_f32_e32 v121, v149, v153
	v_add_f32_e32 v118, v118, v154
	v_add_f32_e32 v119, v119, v155
	v_add_f32_e32 v120, v120, v156
	v_add_f32_e32 v121, v121, v157
	v_add_f32_e32 v118, v118, v158
	v_add_f32_e32 v119, v119, v159
	v_add_f32_e32 v120, v120, v160
	v_add_f32_e32 v121, v121, v161
	v_add_f32_e32 v122, v162, v166
	v_add_f32_e32 v123, v163, v167
	v_add_f32_e32 v124, v164, v168
	v_add_f32_e32 v125, v165, v169
	v_add_f32_e32 v122, v122, v170
	v_add_f32_e32 v123, v123, v171
	v_add_f32_e32 v124, v124, v172
	v_add_f32_e32 v125, v125, v173
	v_add_f32_e32 v122, v122, v174
	v_add_f32_e32 v123, v123, v175
	v_add_f32_e32 v124, v124, v176
	v_add_f32_e32 v125, v125, v177
	v_add_f32_e32 v126, v178, v182
	v_add_f32_e32 v127, v179, v183
	v_add_f32_e32 v128, v180, v184
	v_add_f32_e32 v129, v181, v185
	v_add_f32_e32 v126, v126, v186
	v_add_f32_e32 v127, v127, v187
	v_add_f32_e32 v128, v128, v188
	v_add_f32_e32 v129, v129, v189
	v_add_f32_e32 v126, v126, v190
	v_add_f32_e32 v127, v127, v191
	v_add_f32_e32 v128, v128, v192
	v_add_f32_e32 v129, v129, v193
	s_branch .Ltail12_epi
.Ltail12_skip:
	s_mov_b64 s[2:3], -1
	s_branch .LBB0_1385
.LBB0_1410:
	s_waitcnt vmcnt(0)
	s_barrier

	.amdhsa_kernel _Z10fwd_kernel4Args
		.amdhsa_group_segment_fixed_size 0
		.amdhsa_private_segment_fixed_size 0
		.amdhsa_kernarg_size 448
		.amdhsa_user_sgpr_count 2
		.amdhsa_user_sgpr_dispatch_ptr 0
		.amdhsa_user_sgpr_queue_ptr 0
		.amdhsa_user_sgpr_kernarg_segment_ptr 1
		.amdhsa_user_sgpr_dispatch_id 0
		.amdhsa_user_sgpr_kernarg_preload_length 0
		.amdhsa_user_sgpr_kernarg_preload_offset 0
		.amdhsa_user_sgpr_private_segment_size 0
		.amdhsa_uses_dynamic_stack 0
		.amdhsa_enable_private_segment 0
		.amdhsa_system_sgpr_workgroup_id_x 1
		.amdhsa_system_sgpr_workgroup_id_y 0
		.amdhsa_system_sgpr_workgroup_id_z 0
		.amdhsa_system_sgpr_workgroup_info 0
		.amdhsa_system_vgpr_workitem_id 0
		.amdhsa_next_free_vgpr 256
		.amdhsa_next_free_sgpr 102
		.amdhsa_accum_offset 256
		.amdhsa_reserve_vcc 1
		.amdhsa_float_round_mode_32 0
		.amdhsa_float_round_mode_16_64 0
		.amdhsa_float_denorm_mode_32 3
		.amdhsa_float_denorm_mode_16_64 3
		.amdhsa_dx10_clamp 1
		.amdhsa_ieee_mode 1
		.amdhsa_fp16_overflow 0
		.amdhsa_tg_split 0
		.amdhsa_exception_fp_ieee_invalid_op 0
		.amdhsa_exception_fp_denorm_src 0
		.amdhsa_exception_fp_ieee_div_zero 0
		.amdhsa_exception_fp_ieee_overflow 0
		.amdhsa_exception_fp_ieee_underflow 0
		.amdhsa_exception_fp_ieee_inexact 0
		.amdhsa_exception_int_div_zero 0
	.end_amdhsa_kernel

amdhsa.kernels:
  - .agpr_count:     0
    .args:
      - .offset:         0
        .size:           192
        .value_kind:     by_value
      - .offset:         192
        .size:           4
        .value_kind:     hidden_block_count_x
      - .offset:         196
        .size:           4
        .value_kind:     hidden_block_count_y
      - .offset:         200
        .size:           4
        .value_kind:     hidden_block_count_z
      - .offset:         204
        .size:           2
        .value_kind:     hidden_group_size_x
      - .offset:         206
        .size:           2
        .value_kind:     hidden_group_size_y
      - .offset:         208
        .size:           2
        .value_kind:     hidden_group_size_z
      - .offset:         210
        .size:           2
        .value_kind:     hidden_remainder_x
      - .offset:         212
        .size:           2
        .value_kind:     hidden_remainder_y
      - .offset:         214
        .size:           2
        .value_kind:     hidden_remainder_z
      - .offset:         232
        .size:           8
        .value_kind:     hidden_global_offset_x
      - .offset:         240
        .size:           8
        .value_kind:     hidden_global_offset_y
      - .offset:         248
        .size:           8
        .value_kind:     hidden_global_offset_z
      - .offset:         256
        .size:           2
        .value_kind:     hidden_grid_dims
      - .offset:         312
        .size:           4
        .value_kind:     hidden_dynamic_lds_size
    .group_segment_fixed_size: 0
    .kernarg_segment_align: 8
    .kernarg_segment_size: 448
    .language:       OpenCL C
    .language_version:
      - 2
      - 0
    .max_flat_workgroup_size: 512
    .name:           _Z10fwd_kernel4Args
    .private_segment_fixed_size: 0
    .sgpr_count:     108
    .sgpr_spill_count: 54
    .symbol:         _Z10fwd_kernel4Args.kd
    .uniform_work_group_size: 1
    .uses_dynamic_stack: false
    .vgpr_count:     256
    .vgpr_spill_count: 0
    .wavefront_size: 64
